# MO8+TRIM+IL+ROT2+Z0b (loop-edge SALU hidden in the previous load segment on top of the best)
# speedup vs baseline: 1.0085x; 1.0017x over previous
.LBB0_138:
	s_ashr_i32 s9, s8, 31
	s_lshl_b64 s[14:15], s[8:9], 21
	s_add_u32 s14, s88, s14
	s_addc_u32 s15, s89, s15
	s_and_b64 s[16:17], s[0:1], exec
	s_cselect_b32 s9, s15, s19
	s_cselect_b32 s44, s14, s18
	s_ashr_i32 s7, s6, 31
	s_lshl_b64 s[16:17], s[6:7], 21
	v_readlane_b32 s7, v255, 31
	s_add_u32 s16, s7, s16
	v_readlane_b32 s7, v255, 32
	s_addc_u32 s17, s7, s17
	s_and_b64 s[24:25], s[0:1], exec
	s_cselect_b32 s7, s17, s23
	s_cselect_b32 s45, s16, s22
	s_add_u32 s18, s18, 0x100080
	s_addc_u32 s19, s19, 0
	s_add_u32 s46, s22, 0x100
	s_addc_u32 s47, s23, 0
	s_mov_b32 s48, -2
	s_add_u32 s22, s18, 0xfff00080
	s_addc_u32 s23, s19, -1
	s_cmp_eq_u32 s48, 60
	s_cselect_b32 s25, s9, s23
	s_cselect_b32 s24, s44, s22
	s_cselect_b32 s23, s7, s47
	s_cselect_b32 s22, s45, s46
.LBB0_139:
	s_add_i32 s49, 0, 0x10000
	s_add_i32 s52, 0, 0x14000
	v_add_u32_e32 v156, s49, v145
	v_add_u32_e32 v172, s52, v145
	ds_read_b128 v[140:143], v156
	ds_read_b128 v[148:151], v156 offset:1024
	ds_read_b128 v[152:155], v156 offset:2048
	ds_read_b128 v[156:159], v156 offset:3072
	ds_read_b128 v[160:163], v172
	ds_read_b128 v[164:167], v172 offset:1024
	ds_read_b128 v[168:171], v172 offset:2048
	ds_read_b128 v[190:193], v172 offset:3072
	v_lshl_add_u64 v[172:173], s[18:19], 0, v[136:137]
	s_add_i32 m0, s31, 0xc000
	ds_read_b128 v[194:197], v147
	ds_read_b128 v[198:201], v147 offset:1024
	ds_read_b128 v[202:205], v147 offset:2048
	ds_read_b128 v[206:209], v147 offset:3072
	ds_read_b128 v[228:231], v147 offset:4096
	ds_read_b128 v[232:235], v147 offset:5120
	ds_read_b128 v[236:239], v147 offset:6144
	ds_read_b128 v[240:243], v147 offset:7168
	global_load_lds_dwordx4 v[172:173], off
	v_lshl_add_u64 v[172:173], s[18:19], 0, v[138:139]
	s_add_i32 m0, s31, 0xe000
	s_nop 0
	global_load_lds_dwordx4 v[172:173], off
	s_cmp_eq_u32 s48, -2
	s_cbranch_scc1 .Lz0_0_0
	s_waitcnt vmcnt(8)
	s_waitcnt lgkmcnt(0)
	s_setprio 1
	s_barrier
	v_mfma_f32_16x16x32_bf16 v[126:129], v[140:143], v[194:197], v[126:129]
	v_mfma_f32_16x16x32_bf16 v[126:129], v[148:151], v[198:201], v[126:129]
	v_mfma_f32_16x16x32_bf16 v[118:121], v[148:151], v[206:209], v[118:121]
	v_mfma_f32_16x16x32_bf16 v[118:121], v[140:143], v[202:205], v[118:121]
	v_mfma_f32_16x16x32_bf16 v[102:105], v[140:143], v[228:231], v[102:105]
	v_mfma_f32_16x16x32_bf16 v[102:105], v[148:151], v[232:235], v[102:105]
	v_mfma_f32_16x16x32_bf16 v[86:89], v[148:151], v[240:243], v[86:89]
	v_mfma_f32_16x16x32_bf16 v[86:89], v[140:143], v[236:239], v[86:89]
	v_mfma_f32_16x16x32_bf16 v[78:81], v[152:155], v[236:239], v[78:81]
	v_mfma_f32_16x16x32_bf16 v[78:81], v[156:159], v[240:243], v[78:81]
	v_mfma_f32_16x16x32_bf16 v[94:97], v[156:159], v[232:235], v[94:97]
	v_mfma_f32_16x16x32_bf16 v[94:97], v[152:155], v[228:231], v[94:97]
	v_mfma_f32_16x16x32_bf16 v[110:113], v[152:155], v[202:205], v[110:113]
	v_mfma_f32_16x16x32_bf16 v[110:113], v[156:159], v[206:209], v[110:113]
	v_mfma_f32_16x16x32_bf16 v[122:125], v[156:159], v[198:201], v[122:125]
	v_mfma_f32_16x16x32_bf16 v[122:125], v[152:155], v[194:197], v[122:125]
	v_mfma_f32_16x16x32_bf16 v[114:117], v[160:163], v[194:197], v[114:117]
	v_mfma_f32_16x16x32_bf16 v[114:117], v[164:167], v[198:201], v[114:117]
	v_mfma_f32_16x16x32_bf16 v[98:101], v[164:167], v[206:209], v[98:101]
	v_mfma_f32_16x16x32_bf16 v[98:101], v[160:163], v[202:205], v[98:101]
	v_mfma_f32_16x16x32_bf16 v[82:85], v[160:163], v[228:231], v[82:85]
	v_mfma_f32_16x16x32_bf16 v[82:85], v[164:167], v[232:235], v[82:85]
	v_mfma_f32_16x16x32_bf16 v[70:73], v[164:167], v[240:243], v[70:73]
	v_mfma_f32_16x16x32_bf16 v[70:73], v[160:163], v[236:239], v[70:73]
	v_mfma_f32_16x16x32_bf16 v[66:69], v[168:171], v[236:239], v[66:69]
	v_mfma_f32_16x16x32_bf16 v[66:69], v[190:193], v[240:243], v[66:69]
	v_mfma_f32_16x16x32_bf16 v[74:77], v[190:193], v[232:235], v[74:77]
	v_mfma_f32_16x16x32_bf16 v[74:77], v[168:171], v[228:231], v[74:77]
	v_mfma_f32_16x16x32_bf16 v[90:93], v[168:171], v[202:205], v[90:93]
	v_mfma_f32_16x16x32_bf16 v[90:93], v[190:193], v[206:209], v[90:93]
	v_mfma_f32_16x16x32_bf16 v[106:109], v[190:193], v[198:201], v[106:109]
	v_mfma_f32_16x16x32_bf16 v[106:109], v[168:171], v[194:197], v[106:109]
	s_barrier
	s_setprio 0

.Lz0_0_1_ret:
	s_add_i32 s49, 0, 0x18000
	s_add_i32 s50, 0, 0x1c000
	v_add_u32_e32 v156, s49, v145
	v_add_u32_e32 v175, s50, v145
	ds_read_b128 v[140:143], v156
	ds_read_b128 v[148:151], v156 offset:1024
	ds_read_b128 v[152:155], v156 offset:2048
	ds_read_b128 v[156:159], v156 offset:3072
	ds_read_b128 v[160:163], v175
	ds_read_b128 v[164:167], v175 offset:1024
	ds_read_b128 v[168:171], v175 offset:2048
	ds_read_b128 v[190:193], v175 offset:3072
	s_add_u32 s24, s24, 0x100000
	s_addc_u32 s25, s25, 0
	s_mov_b32 m0, s37
	v_lshl_add_u64 v[244:245], s[24:25], 0, v[134:135]
	ds_read_b128 v[194:197], v147 offset:32768
	ds_read_b128 v[198:201], v147 offset:33792
	ds_read_b128 v[202:205], v147 offset:34816
	ds_read_b128 v[206:209], v147 offset:35840
	ds_read_b128 v[228:231], v147 offset:36864
	ds_read_b128 v[232:235], v147 offset:37888
	ds_read_b128 v[236:239], v147 offset:38912
	ds_read_b128 v[240:243], v147 offset:39936
	global_load_lds_dwordx4 v[244:245], off
	v_lshl_add_u64 v[244:245], s[24:25], 0, v[132:133]
	s_mov_b32 m0, s38
	s_nop 0
	global_load_lds_dwordx4 v[244:245], off
	s_waitcnt vmcnt(8)
	s_waitcnt lgkmcnt(0)
	s_setprio 1
	s_barrier
	v_mfma_f32_16x16x32_bf16 v[126:129], v[140:143], v[194:197], v[126:129]
	v_mfma_f32_16x16x32_bf16 v[126:129], v[148:151], v[198:201], v[126:129]
	v_mfma_f32_16x16x32_bf16 v[118:121], v[148:151], v[206:209], v[118:121]
	v_mfma_f32_16x16x32_bf16 v[118:121], v[140:143], v[202:205], v[118:121]
	v_mfma_f32_16x16x32_bf16 v[102:105], v[140:143], v[228:231], v[102:105]
	v_mfma_f32_16x16x32_bf16 v[102:105], v[148:151], v[232:235], v[102:105]
	v_mfma_f32_16x16x32_bf16 v[86:89], v[148:151], v[240:243], v[86:89]
	v_mfma_f32_16x16x32_bf16 v[86:89], v[140:143], v[236:239], v[86:89]
	v_mfma_f32_16x16x32_bf16 v[78:81], v[152:155], v[236:239], v[78:81]
	v_mfma_f32_16x16x32_bf16 v[78:81], v[156:159], v[240:243], v[78:81]
	v_mfma_f32_16x16x32_bf16 v[94:97], v[156:159], v[232:235], v[94:97]
	v_mfma_f32_16x16x32_bf16 v[94:97], v[152:155], v[228:231], v[94:97]
	v_mfma_f32_16x16x32_bf16 v[110:113], v[152:155], v[202:205], v[110:113]
	v_mfma_f32_16x16x32_bf16 v[110:113], v[156:159], v[206:209], v[110:113]
	v_mfma_f32_16x16x32_bf16 v[122:125], v[156:159], v[198:201], v[122:125]
	v_mfma_f32_16x16x32_bf16 v[122:125], v[152:155], v[194:197], v[122:125]
	v_mfma_f32_16x16x32_bf16 v[114:117], v[160:163], v[194:197], v[114:117]
	v_mfma_f32_16x16x32_bf16 v[114:117], v[164:167], v[198:201], v[114:117]
	v_mfma_f32_16x16x32_bf16 v[98:101], v[164:167], v[206:209], v[98:101]
	v_mfma_f32_16x16x32_bf16 v[98:101], v[160:163], v[202:205], v[98:101]
	v_mfma_f32_16x16x32_bf16 v[82:85], v[160:163], v[228:231], v[82:85]
	v_mfma_f32_16x16x32_bf16 v[82:85], v[164:167], v[232:235], v[82:85]
	v_mfma_f32_16x16x32_bf16 v[70:73], v[164:167], v[240:243], v[70:73]
	v_mfma_f32_16x16x32_bf16 v[70:73], v[160:163], v[236:239], v[70:73]
	v_mfma_f32_16x16x32_bf16 v[66:69], v[168:171], v[236:239], v[66:69]
	v_mfma_f32_16x16x32_bf16 v[66:69], v[190:193], v[240:243], v[66:69]
	v_mfma_f32_16x16x32_bf16 v[74:77], v[190:193], v[232:235], v[74:77]
	v_mfma_f32_16x16x32_bf16 v[74:77], v[168:171], v[228:231], v[74:77]
	v_mfma_f32_16x16x32_bf16 v[90:93], v[168:171], v[202:205], v[90:93]
	v_mfma_f32_16x16x32_bf16 v[90:93], v[190:193], v[206:209], v[90:93]
	v_mfma_f32_16x16x32_bf16 v[106:109], v[190:193], v[198:201], v[106:109]
	v_mfma_f32_16x16x32_bf16 v[106:109], v[168:171], v[194:197], v[106:109]
	s_barrier
	s_setprio 0
	s_add_i32 s24, s49, s26
	v_lshl_add_u64 v[172:173], v[172:173], 0, s[34:35]
	s_mov_b32 m0, s24
	s_nop 0
	global_load_lds_dwordx4 v[172:173], off
	ds_read_b128 v[194:197], v147 offset:49152
	ds_read_b128 v[198:201], v147 offset:50176
	s_add_i32 m0, s24, 0x2000
	s_add_u32 s22, s22, 0x100080
	v_lshl_add_u64 v[172:173], v[178:179], 0, s[34:35]
	s_addc_u32 s23, s23, 0
	s_add_i32 s24, s50, s26
	global_load_lds_dwordx4 v[172:173], off
	ds_read_b128 v[202:205], v147 offset:51200
	ds_read_b128 v[206:209], v147 offset:52224
	v_lshl_add_u64 v[172:173], s[22:23], 0, v[0:1]
	s_mov_b32 m0, s24
	s_nop 0
	global_load_lds_dwordx4 v[172:173], off
	ds_read_b128 v[228:231], v147 offset:53248
	ds_read_b128 v[232:235], v147 offset:54272
	v_lshl_add_u64 v[172:173], s[22:23], 0, v[130:131]
	s_add_i32 m0, s24, 0x2000
	s_nop 0
	global_load_lds_dwordx4 v[172:173], off
	ds_read_b128 v[236:239], v147 offset:55296
	ds_read_b128 v[240:243], v147 offset:56320
	v_lshl_add_u64 v[172:173], v[180:181], 0, s[34:35]
	s_mov_b32 m0, s39
	s_nop 0
	global_load_lds_dwordx4 v[172:173], off
	s_add_i32 s48, s48, 2
	s_add_u32 s18, s18, 0x100
	s_addc_u32 s19, s19, 0
	s_add_u32 s46, s46, 0x100
	s_addc_u32 s47, s47, 0
	s_add_u32 s22, s18, 0xfff00080
	s_addc_u32 s23, s19, -1
	s_cmp_eq_u32 s48, 60
	s_cselect_b32 s25, s9, s23
	s_cselect_b32 s24, s44, s22
	s_cselect_b32 s23, s7, s47
	s_cselect_b32 s22, s45, s46
	v_lshl_add_u64 v[172:173], v[210:211], 0, s[34:35]
	s_mov_b32 m0, s40
	s_nop 0
	global_load_lds_dwordx4 v[172:173], off
	s_waitcnt vmcnt(8)
	s_waitcnt lgkmcnt(0)
	s_setprio 1
	s_barrier
	v_mfma_f32_16x16x32_bf16 v[62:65], v[140:143], v[194:197], v[62:65]
	v_mfma_f32_16x16x32_bf16 v[62:65], v[148:151], v[198:201], v[62:65]
	v_mfma_f32_16x16x32_bf16 v[54:57], v[148:151], v[206:209], v[54:57]
	v_mfma_f32_16x16x32_bf16 v[54:57], v[140:143], v[202:205], v[54:57]
	v_mfma_f32_16x16x32_bf16 v[38:41], v[140:143], v[228:231], v[38:41]
	v_mfma_f32_16x16x32_bf16 v[38:41], v[148:151], v[232:235], v[38:41]
	v_mfma_f32_16x16x32_bf16 v[22:25], v[148:151], v[240:243], v[22:25]
	v_mfma_f32_16x16x32_bf16 v[22:25], v[140:143], v[236:239], v[22:25]
	v_mfma_f32_16x16x32_bf16 v[14:17], v[152:155], v[236:239], v[14:17]
	v_mfma_f32_16x16x32_bf16 v[14:17], v[156:159], v[240:243], v[14:17]
	v_mfma_f32_16x16x32_bf16 v[30:33], v[156:159], v[232:235], v[30:33]
	v_mfma_f32_16x16x32_bf16 v[30:33], v[152:155], v[228:231], v[30:33]
	v_mfma_f32_16x16x32_bf16 v[46:49], v[152:155], v[202:205], v[46:49]
	v_mfma_f32_16x16x32_bf16 v[46:49], v[156:159], v[206:209], v[46:49]
	v_mfma_f32_16x16x32_bf16 v[58:61], v[156:159], v[198:201], v[58:61]
	v_mfma_f32_16x16x32_bf16 v[58:61], v[152:155], v[194:197], v[58:61]
	v_mfma_f32_16x16x32_bf16 v[50:53], v[160:163], v[194:197], v[50:53]
	v_mfma_f32_16x16x32_bf16 v[50:53], v[164:167], v[198:201], v[50:53]
	v_mfma_f32_16x16x32_bf16 v[34:37], v[164:167], v[206:209], v[34:37]
	v_mfma_f32_16x16x32_bf16 v[34:37], v[160:163], v[202:205], v[34:37]
	v_mfma_f32_16x16x32_bf16 v[18:21], v[160:163], v[228:231], v[18:21]
	v_mfma_f32_16x16x32_bf16 v[18:21], v[164:167], v[232:235], v[18:21]
	v_mfma_f32_16x16x32_bf16 v[6:9], v[164:167], v[240:243], v[6:9]
	v_mfma_f32_16x16x32_bf16 v[6:9], v[160:163], v[236:239], v[6:9]
	v_mfma_f32_16x16x32_bf16 v[2:5], v[168:171], v[236:239], v[2:5]
	v_mfma_f32_16x16x32_bf16 v[2:5], v[190:193], v[240:243], v[2:5]
	v_mfma_f32_16x16x32_bf16 v[10:13], v[190:193], v[232:235], v[10:13]
	v_mfma_f32_16x16x32_bf16 v[10:13], v[168:171], v[228:231], v[10:13]
	v_mfma_f32_16x16x32_bf16 v[26:29], v[168:171], v[202:205], v[26:29]
	v_mfma_f32_16x16x32_bf16 v[26:29], v[190:193], v[206:209], v[26:29]
	v_mfma_f32_16x16x32_bf16 v[42:45], v[190:193], v[198:201], v[42:45]
	v_mfma_f32_16x16x32_bf16 v[42:45], v[168:171], v[194:197], v[42:45]
	s_barrier
	s_setprio 0
	s_cmp_gt_u32 s48, 61
	s_cbranch_scc0 .LBB0_139
	s_and_b64 vcc, exec, s[4:5]
	s_cbranch_vccz .LBB0_142
	s_barrier

.LBB0_574:
	s_ashr_i32 s9, s8, 31
	s_lshl_b64 s[14:15], s[8:9], 21
	v_readlane_b32 s7, v254, 15
	s_add_u32 s14, s7, s14
	v_readlane_b32 s7, v254, 16
	s_addc_u32 s15, s7, s15
	s_and_b64 s[16:17], s[0:1], exec
	s_cselect_b32 s9, s15, s19
	s_cselect_b32 s48, s14, s18
	s_ashr_i32 s7, s6, 31
	s_lshl_b64 s[16:17], s[6:7], 21
	s_add_u32 s16, s26, s16
	s_addc_u32 s17, s31, s17
	s_and_b64 s[24:25], s[0:1], exec
	s_cselect_b32 s7, s17, s23
	s_cselect_b32 s49, s16, s22
	s_add_u32 s18, s18, 0x100080
	s_addc_u32 s19, s19, 0
	s_add_u32 s50, s22, 0x100
	s_addc_u32 s51, s23, 0
	s_mov_b32 s52, -2
	s_add_u32 s22, s18, 0xfff00080
	s_addc_u32 s23, s19, -1
	s_cmp_eq_u32 s52, 60
	s_cselect_b32 s25, s9, s23
	s_cselect_b32 s24, s48, s22
	s_cselect_b32 s23, s7, s51
	s_cselect_b32 s22, s49, s50
.LBB0_575:
	s_add_i32 s53, 0, 0x10000
	v_add_u32_e32 v140, s53, v143
	s_add_i32 s56, 0, 0x14000
	ds_read_b128 v[146:149], v140
	ds_read_b128 v[150:153], v140 offset:1024
	ds_read_b128 v[154:157], v140 offset:2048
	ds_read_b128 v[158:161], v140 offset:3072
	v_add_u32_e32 v140, s56, v143
	ds_read_b128 v[162:165], v140
	ds_read_b128 v[166:169], v140 offset:1024
	ds_read_b128 v[170:173], v140 offset:2048
	ds_read_b128 v[178:181], v140 offset:3072
	v_lshl_add_u64 v[140:141], s[18:19], 0, v[136:137]
	s_add_i32 m0, s39, 0xc000
	ds_read_b128 v[190:193], v145
	ds_read_b128 v[194:197], v145 offset:1024
	ds_read_b128 v[198:201], v145 offset:2048
	ds_read_b128 v[202:205], v145 offset:3072
	ds_read_b128 v[206:209], v145 offset:4096
	ds_read_b128 v[228:231], v145 offset:5120
	ds_read_b128 v[232:235], v145 offset:6144
	ds_read_b128 v[236:239], v145 offset:7168
	global_load_lds_dwordx4 v[140:141], off
	v_lshl_add_u64 v[140:141], s[18:19], 0, v[138:139]
	s_add_i32 m0, s39, 0xe000
	s_nop 0
	global_load_lds_dwordx4 v[140:141], off
	s_cmp_eq_u32 s52, -2
	s_cbranch_scc1 .Lz0_1_0
	s_waitcnt vmcnt(8)
	s_waitcnt lgkmcnt(0)
	s_setprio 1
	s_barrier
	v_mfma_f32_16x16x32_bf16 v[126:129], v[146:149], v[190:193], v[126:129]
	v_mfma_f32_16x16x32_bf16 v[126:129], v[150:153], v[194:197], v[126:129]
	v_mfma_f32_16x16x32_bf16 v[118:121], v[150:153], v[202:205], v[118:121]
	v_mfma_f32_16x16x32_bf16 v[118:121], v[146:149], v[198:201], v[118:121]
	v_mfma_f32_16x16x32_bf16 v[102:105], v[146:149], v[206:209], v[102:105]
	v_mfma_f32_16x16x32_bf16 v[102:105], v[150:153], v[228:231], v[102:105]
	v_mfma_f32_16x16x32_bf16 v[86:89], v[150:153], v[236:239], v[86:89]
	v_mfma_f32_16x16x32_bf16 v[86:89], v[146:149], v[232:235], v[86:89]
	v_mfma_f32_16x16x32_bf16 v[78:81], v[154:157], v[232:235], v[78:81]
	v_mfma_f32_16x16x32_bf16 v[78:81], v[158:161], v[236:239], v[78:81]
	v_mfma_f32_16x16x32_bf16 v[94:97], v[158:161], v[228:231], v[94:97]
	v_mfma_f32_16x16x32_bf16 v[94:97], v[154:157], v[206:209], v[94:97]
	v_mfma_f32_16x16x32_bf16 v[110:113], v[154:157], v[198:201], v[110:113]
	v_mfma_f32_16x16x32_bf16 v[110:113], v[158:161], v[202:205], v[110:113]
	v_mfma_f32_16x16x32_bf16 v[122:125], v[158:161], v[194:197], v[122:125]
	v_mfma_f32_16x16x32_bf16 v[122:125], v[154:157], v[190:193], v[122:125]
	v_mfma_f32_16x16x32_bf16 v[114:117], v[162:165], v[190:193], v[114:117]
	v_mfma_f32_16x16x32_bf16 v[114:117], v[166:169], v[194:197], v[114:117]
	v_mfma_f32_16x16x32_bf16 v[98:101], v[166:169], v[202:205], v[98:101]
	v_mfma_f32_16x16x32_bf16 v[98:101], v[162:165], v[198:201], v[98:101]
	v_mfma_f32_16x16x32_bf16 v[82:85], v[162:165], v[206:209], v[82:85]
	v_mfma_f32_16x16x32_bf16 v[82:85], v[166:169], v[228:231], v[82:85]
	v_mfma_f32_16x16x32_bf16 v[70:73], v[166:169], v[236:239], v[70:73]
	v_mfma_f32_16x16x32_bf16 v[70:73], v[162:165], v[232:235], v[70:73]
	v_mfma_f32_16x16x32_bf16 v[66:69], v[170:173], v[232:235], v[66:69]
	v_mfma_f32_16x16x32_bf16 v[66:69], v[178:181], v[236:239], v[66:69]
	v_mfma_f32_16x16x32_bf16 v[74:77], v[178:181], v[228:231], v[74:77]
	v_mfma_f32_16x16x32_bf16 v[74:77], v[170:173], v[206:209], v[74:77]
	v_mfma_f32_16x16x32_bf16 v[90:93], v[170:173], v[198:201], v[90:93]
	v_mfma_f32_16x16x32_bf16 v[90:93], v[178:181], v[202:205], v[90:93]
	v_mfma_f32_16x16x32_bf16 v[106:109], v[178:181], v[194:197], v[106:109]
	v_mfma_f32_16x16x32_bf16 v[106:109], v[170:173], v[190:193], v[106:109]
	s_barrier
	s_setprio 0

.Lz0_1_1_ret:
	s_add_i32 s53, 0, 0x18000
	s_add_i32 s54, 0, 0x1c000
	v_add_u32_e32 v158, s53, v143
	v_add_u32_e32 v175, s54, v143
	ds_read_b128 v[146:149], v158
	ds_read_b128 v[150:153], v158 offset:1024
	ds_read_b128 v[154:157], v158 offset:2048
	ds_read_b128 v[158:161], v158 offset:3072
	ds_read_b128 v[162:165], v175
	ds_read_b128 v[166:169], v175 offset:1024
	ds_read_b128 v[170:173], v175 offset:2048
	ds_read_b128 v[178:181], v175 offset:3072
	s_add_u32 s24, s24, 0x100000
	s_addc_u32 s25, s25, 0
	s_mov_b32 m0, s41
	v_lshl_add_u64 v[226:227], s[24:25], 0, v[134:135]
	ds_read_b128 v[190:193], v145 offset:32768
	ds_read_b128 v[194:197], v145 offset:33792
	ds_read_b128 v[198:201], v145 offset:34816
	ds_read_b128 v[202:205], v145 offset:35840
	ds_read_b128 v[206:209], v145 offset:36864
	ds_read_b128 v[228:231], v145 offset:37888
	ds_read_b128 v[232:235], v145 offset:38912
	ds_read_b128 v[236:239], v145 offset:39936
	global_load_lds_dwordx4 v[226:227], off
	v_lshl_add_u64 v[226:227], s[24:25], 0, v[132:133]
	s_mov_b32 m0, s42
	s_nop 0
	global_load_lds_dwordx4 v[226:227], off
	s_waitcnt vmcnt(8)
	s_waitcnt lgkmcnt(0)
	s_setprio 1
	s_barrier
	v_mfma_f32_16x16x32_bf16 v[126:129], v[146:149], v[190:193], v[126:129]
	v_mfma_f32_16x16x32_bf16 v[126:129], v[150:153], v[194:197], v[126:129]
	v_mfma_f32_16x16x32_bf16 v[118:121], v[150:153], v[202:205], v[118:121]
	v_mfma_f32_16x16x32_bf16 v[118:121], v[146:149], v[198:201], v[118:121]
	v_mfma_f32_16x16x32_bf16 v[102:105], v[146:149], v[206:209], v[102:105]
	v_mfma_f32_16x16x32_bf16 v[102:105], v[150:153], v[228:231], v[102:105]
	v_mfma_f32_16x16x32_bf16 v[86:89], v[150:153], v[236:239], v[86:89]
	v_mfma_f32_16x16x32_bf16 v[86:89], v[146:149], v[232:235], v[86:89]
	v_mfma_f32_16x16x32_bf16 v[78:81], v[154:157], v[232:235], v[78:81]
	v_mfma_f32_16x16x32_bf16 v[78:81], v[158:161], v[236:239], v[78:81]
	v_mfma_f32_16x16x32_bf16 v[94:97], v[158:161], v[228:231], v[94:97]
	v_mfma_f32_16x16x32_bf16 v[94:97], v[154:157], v[206:209], v[94:97]
	v_mfma_f32_16x16x32_bf16 v[110:113], v[154:157], v[198:201], v[110:113]
	v_mfma_f32_16x16x32_bf16 v[110:113], v[158:161], v[202:205], v[110:113]
	v_mfma_f32_16x16x32_bf16 v[122:125], v[158:161], v[194:197], v[122:125]
	v_mfma_f32_16x16x32_bf16 v[122:125], v[154:157], v[190:193], v[122:125]
	v_mfma_f32_16x16x32_bf16 v[114:117], v[162:165], v[190:193], v[114:117]
	v_mfma_f32_16x16x32_bf16 v[114:117], v[166:169], v[194:197], v[114:117]
	v_mfma_f32_16x16x32_bf16 v[98:101], v[166:169], v[202:205], v[98:101]
	v_mfma_f32_16x16x32_bf16 v[98:101], v[162:165], v[198:201], v[98:101]
	v_mfma_f32_16x16x32_bf16 v[82:85], v[162:165], v[206:209], v[82:85]
	v_mfma_f32_16x16x32_bf16 v[82:85], v[166:169], v[228:231], v[82:85]
	v_mfma_f32_16x16x32_bf16 v[70:73], v[166:169], v[236:239], v[70:73]
	v_mfma_f32_16x16x32_bf16 v[70:73], v[162:165], v[232:235], v[70:73]
	v_mfma_f32_16x16x32_bf16 v[66:69], v[170:173], v[232:235], v[66:69]
	v_mfma_f32_16x16x32_bf16 v[66:69], v[178:181], v[236:239], v[66:69]
	v_mfma_f32_16x16x32_bf16 v[74:77], v[178:181], v[228:231], v[74:77]
	v_mfma_f32_16x16x32_bf16 v[74:77], v[170:173], v[206:209], v[74:77]
	v_mfma_f32_16x16x32_bf16 v[90:93], v[170:173], v[198:201], v[90:93]
	v_mfma_f32_16x16x32_bf16 v[90:93], v[178:181], v[202:205], v[90:93]
	v_mfma_f32_16x16x32_bf16 v[106:109], v[178:181], v[194:197], v[106:109]
	v_mfma_f32_16x16x32_bf16 v[106:109], v[170:173], v[190:193], v[106:109]
	s_barrier
	s_setprio 0
	s_add_i32 s24, s53, s38
	v_lshl_add_u64 v[140:141], v[140:141], 0, s[34:35]
	s_mov_b32 m0, s24
	s_nop 0
	global_load_lds_dwordx4 v[140:141], off
	ds_read_b128 v[190:193], v145 offset:49152
	ds_read_b128 v[194:197], v145 offset:50176
	s_add_i32 m0, s24, 0x2000
	s_add_u32 s22, s22, 0x100080
	v_lshl_add_u64 v[140:141], v[186:187], 0, s[34:35]
	s_addc_u32 s23, s23, 0
	s_add_i32 s24, s54, s38
	global_load_lds_dwordx4 v[140:141], off
	ds_read_b128 v[198:201], v145 offset:51200
	ds_read_b128 v[202:205], v145 offset:52224
	v_lshl_add_u64 v[140:141], s[22:23], 0, v[0:1]
	s_mov_b32 m0, s24
	s_nop 0
	global_load_lds_dwordx4 v[140:141], off
	ds_read_b128 v[206:209], v145 offset:53248
	ds_read_b128 v[228:231], v145 offset:54272
	v_lshl_add_u64 v[140:141], s[22:23], 0, v[130:131]
	s_add_i32 m0, s24, 0x2000
	s_nop 0
	global_load_lds_dwordx4 v[140:141], off
	ds_read_b128 v[232:235], v145 offset:55296
	ds_read_b128 v[236:239], v145 offset:56320
	v_lshl_add_u64 v[140:141], v[188:189], 0, s[34:35]
	s_mov_b32 m0, s43
	s_nop 0
	global_load_lds_dwordx4 v[140:141], off
	s_add_i32 s52, s52, 2
	s_add_u32 s18, s18, 0x100
	s_addc_u32 s19, s19, 0
	s_add_u32 s50, s50, 0x100
	s_addc_u32 s51, s51, 0
	s_add_u32 s22, s18, 0xfff00080
	s_addc_u32 s23, s19, -1
	s_cmp_eq_u32 s52, 60
	s_cselect_b32 s25, s9, s23
	s_cselect_b32 s24, s48, s22
	s_cselect_b32 s23, s7, s51
	s_cselect_b32 s22, s49, s50
	v_lshl_add_u64 v[140:141], v[210:211], 0, s[34:35]
	s_mov_b32 m0, s44
	s_nop 0
	global_load_lds_dwordx4 v[140:141], off
	s_waitcnt vmcnt(8)
	s_waitcnt lgkmcnt(0)
	s_setprio 1
	s_barrier
	v_mfma_f32_16x16x32_bf16 v[62:65], v[146:149], v[190:193], v[62:65]
	v_mfma_f32_16x16x32_bf16 v[62:65], v[150:153], v[194:197], v[62:65]
	v_mfma_f32_16x16x32_bf16 v[54:57], v[150:153], v[202:205], v[54:57]
	v_mfma_f32_16x16x32_bf16 v[54:57], v[146:149], v[198:201], v[54:57]
	v_mfma_f32_16x16x32_bf16 v[38:41], v[146:149], v[206:209], v[38:41]
	v_mfma_f32_16x16x32_bf16 v[38:41], v[150:153], v[228:231], v[38:41]
	v_mfma_f32_16x16x32_bf16 v[22:25], v[150:153], v[236:239], v[22:25]
	v_mfma_f32_16x16x32_bf16 v[22:25], v[146:149], v[232:235], v[22:25]
	v_mfma_f32_16x16x32_bf16 v[14:17], v[154:157], v[232:235], v[14:17]
	v_mfma_f32_16x16x32_bf16 v[14:17], v[158:161], v[236:239], v[14:17]
	v_mfma_f32_16x16x32_bf16 v[30:33], v[158:161], v[228:231], v[30:33]
	v_mfma_f32_16x16x32_bf16 v[30:33], v[154:157], v[206:209], v[30:33]
	v_mfma_f32_16x16x32_bf16 v[46:49], v[154:157], v[198:201], v[46:49]
	v_mfma_f32_16x16x32_bf16 v[46:49], v[158:161], v[202:205], v[46:49]
	v_mfma_f32_16x16x32_bf16 v[58:61], v[158:161], v[194:197], v[58:61]
	v_mfma_f32_16x16x32_bf16 v[58:61], v[154:157], v[190:193], v[58:61]
	v_mfma_f32_16x16x32_bf16 v[50:53], v[162:165], v[190:193], v[50:53]
	v_mfma_f32_16x16x32_bf16 v[50:53], v[166:169], v[194:197], v[50:53]
	v_mfma_f32_16x16x32_bf16 v[34:37], v[166:169], v[202:205], v[34:37]
	v_mfma_f32_16x16x32_bf16 v[34:37], v[162:165], v[198:201], v[34:37]
	v_mfma_f32_16x16x32_bf16 v[18:21], v[162:165], v[206:209], v[18:21]
	v_mfma_f32_16x16x32_bf16 v[18:21], v[166:169], v[228:231], v[18:21]
	v_mfma_f32_16x16x32_bf16 v[6:9], v[166:169], v[236:239], v[6:9]
	v_mfma_f32_16x16x32_bf16 v[6:9], v[162:165], v[232:235], v[6:9]
	v_mfma_f32_16x16x32_bf16 v[2:5], v[170:173], v[232:235], v[2:5]
	v_mfma_f32_16x16x32_bf16 v[2:5], v[178:181], v[236:239], v[2:5]
	v_mfma_f32_16x16x32_bf16 v[10:13], v[178:181], v[228:231], v[10:13]
	v_mfma_f32_16x16x32_bf16 v[10:13], v[170:173], v[206:209], v[10:13]
	v_mfma_f32_16x16x32_bf16 v[26:29], v[170:173], v[198:201], v[26:29]
	v_mfma_f32_16x16x32_bf16 v[26:29], v[178:181], v[202:205], v[26:29]
	v_mfma_f32_16x16x32_bf16 v[42:45], v[178:181], v[194:197], v[42:45]
	v_mfma_f32_16x16x32_bf16 v[42:45], v[170:173], v[190:193], v[42:45]
	s_barrier
	s_setprio 0
	s_cmp_gt_u32 s52, 61
	s_cbranch_scc0 .LBB0_575
	s_and_b64 vcc, exec, s[4:5]
	s_cbranch_vccz .LBB0_578
	s_barrier

.LBB0_720:
	s_ashr_i32 s7, s6, 31
	s_lshl_b64 s[8:9], s[6:7], 21
	s_add_u32 s8, s88, s8
	s_addc_u32 s9, s89, s9
	s_and_b64 s[14:15], s[38:39], exec
	s_cselect_b32 s7, s9, s17
	s_cselect_b32 s48, s8, s16
	s_ashr_i32 s5, s4, 31
	s_lshl_b64 s[14:15], s[4:5], 21
	s_add_u32 s14, s24, s14
	s_addc_u32 s15, s25, s15
	s_and_b64 s[22:23], s[38:39], exec
	s_cselect_b32 s5, s15, s19
	s_cselect_b32 s49, s14, s18
	s_add_u32 s16, s16, 0x100080
	s_addc_u32 s17, s17, 0
	s_add_u32 s50, s18, 0x100
	s_addc_u32 s51, s19, 0
	s_mov_b32 s52, -2
	s_add_u32 s18, s16, 0xfff00080
	s_addc_u32 s19, s17, -1
	s_cmp_eq_u32 s52, 60
	s_cselect_b32 s23, s7, s19
	s_cselect_b32 s22, s48, s18
	s_cselect_b32 s19, s5, s51
	s_cselect_b32 s18, s49, s50
.LBB0_721:
	s_add_i32 s53, 0, 0x10000
	v_add_u32_e32 v140, s53, v143
	s_add_i32 s56, 0, 0x14000
	ds_read_b128 v[146:149], v140
	ds_read_b128 v[150:153], v140 offset:1024
	ds_read_b128 v[154:157], v140 offset:2048
	ds_read_b128 v[158:161], v140 offset:3072
	v_add_u32_e32 v140, s56, v143
	ds_read_b128 v[162:165], v140
	ds_read_b128 v[166:169], v140 offset:1024
	ds_read_b128 v[170:173], v140 offset:2048
	ds_read_b128 v[178:181], v140 offset:3072
	v_lshl_add_u64 v[140:141], s[16:17], 0, v[136:137]
	s_add_i32 m0, s31, 0xc000
	ds_read_b128 v[190:193], v145
	ds_read_b128 v[194:197], v145 offset:1024
	ds_read_b128 v[198:201], v145 offset:2048
	ds_read_b128 v[202:205], v145 offset:3072
	ds_read_b128 v[206:209], v145 offset:4096
	ds_read_b128 v[228:231], v145 offset:5120
	ds_read_b128 v[232:235], v145 offset:6144
	ds_read_b128 v[236:239], v145 offset:7168
	global_load_lds_dwordx4 v[140:141], off
	v_lshl_add_u64 v[140:141], s[16:17], 0, v[138:139]
	s_add_i32 m0, s31, 0xe000
	s_nop 0
	global_load_lds_dwordx4 v[140:141], off
	s_cmp_eq_u32 s52, -2
	s_cbranch_scc1 .Lz0_2_0
	s_waitcnt vmcnt(8)
	s_waitcnt lgkmcnt(0)
	s_setprio 1
	s_barrier
	v_mfma_f32_16x16x32_bf16 v[126:129], v[146:149], v[190:193], v[126:129]
	v_mfma_f32_16x16x32_bf16 v[126:129], v[150:153], v[194:197], v[126:129]
	v_mfma_f32_16x16x32_bf16 v[110:113], v[150:153], v[202:205], v[110:113]
	v_mfma_f32_16x16x32_bf16 v[110:113], v[146:149], v[198:201], v[110:113]
	v_mfma_f32_16x16x32_bf16 v[94:97], v[146:149], v[206:209], v[94:97]
	v_mfma_f32_16x16x32_bf16 v[94:97], v[150:153], v[228:231], v[94:97]
	v_mfma_f32_16x16x32_bf16 v[78:81], v[150:153], v[236:239], v[78:81]
	v_mfma_f32_16x16x32_bf16 v[78:81], v[146:149], v[232:235], v[78:81]
	v_mfma_f32_16x16x32_bf16 v[70:73], v[154:157], v[232:235], v[70:73]
	v_mfma_f32_16x16x32_bf16 v[70:73], v[158:161], v[236:239], v[70:73]
	v_mfma_f32_16x16x32_bf16 v[86:89], v[158:161], v[228:231], v[86:89]
	v_mfma_f32_16x16x32_bf16 v[86:89], v[154:157], v[206:209], v[86:89]
	v_mfma_f32_16x16x32_bf16 v[102:105], v[154:157], v[198:201], v[102:105]
	v_mfma_f32_16x16x32_bf16 v[102:105], v[158:161], v[202:205], v[102:105]
	v_mfma_f32_16x16x32_bf16 v[118:121], v[158:161], v[194:197], v[118:121]
	v_mfma_f32_16x16x32_bf16 v[118:121], v[154:157], v[190:193], v[118:121]
	v_mfma_f32_16x16x32_bf16 v[122:125], v[162:165], v[190:193], v[122:125]
	v_mfma_f32_16x16x32_bf16 v[122:125], v[166:169], v[194:197], v[122:125]
	v_mfma_f32_16x16x32_bf16 v[106:109], v[166:169], v[202:205], v[106:109]
	v_mfma_f32_16x16x32_bf16 v[106:109], v[162:165], v[198:201], v[106:109]
	v_mfma_f32_16x16x32_bf16 v[90:93], v[162:165], v[206:209], v[90:93]
	v_mfma_f32_16x16x32_bf16 v[90:93], v[166:169], v[228:231], v[90:93]
	v_mfma_f32_16x16x32_bf16 v[74:77], v[166:169], v[236:239], v[74:77]
	v_mfma_f32_16x16x32_bf16 v[74:77], v[162:165], v[232:235], v[74:77]
	v_mfma_f32_16x16x32_bf16 v[66:69], v[170:173], v[232:235], v[66:69]
	v_mfma_f32_16x16x32_bf16 v[66:69], v[178:181], v[236:239], v[66:69]
	v_mfma_f32_16x16x32_bf16 v[82:85], v[178:181], v[228:231], v[82:85]
	v_mfma_f32_16x16x32_bf16 v[82:85], v[170:173], v[206:209], v[82:85]
	v_mfma_f32_16x16x32_bf16 v[98:101], v[170:173], v[198:201], v[98:101]
	v_mfma_f32_16x16x32_bf16 v[98:101], v[178:181], v[202:205], v[98:101]
	v_mfma_f32_16x16x32_bf16 v[114:117], v[178:181], v[194:197], v[114:117]
	v_mfma_f32_16x16x32_bf16 v[114:117], v[170:173], v[190:193], v[114:117]
	s_barrier
	s_setprio 0

.Lz0_2_1_ret:
	s_add_i32 s53, 0, 0x18000
	s_add_i32 s54, 0, 0x1c000
	v_add_u32_e32 v158, s53, v143
	v_add_u32_e32 v175, s54, v143
	ds_read_b128 v[146:149], v158
	ds_read_b128 v[150:153], v158 offset:1024
	ds_read_b128 v[154:157], v158 offset:2048
	ds_read_b128 v[158:161], v158 offset:3072
	ds_read_b128 v[162:165], v175
	ds_read_b128 v[166:169], v175 offset:1024
	ds_read_b128 v[170:173], v175 offset:2048
	ds_read_b128 v[178:181], v175 offset:3072
	s_add_u32 s22, s22, 0x100000
	s_addc_u32 s23, s23, 0
	s_mov_b32 m0, s41
	v_lshl_add_u64 v[226:227], s[22:23], 0, v[134:135]
	ds_read_b128 v[190:193], v145 offset:32768
	ds_read_b128 v[194:197], v145 offset:33792
	ds_read_b128 v[198:201], v145 offset:34816
	ds_read_b128 v[202:205], v145 offset:35840
	ds_read_b128 v[206:209], v145 offset:36864
	ds_read_b128 v[228:231], v145 offset:37888
	ds_read_b128 v[232:235], v145 offset:38912
	ds_read_b128 v[236:239], v145 offset:39936
	global_load_lds_dwordx4 v[226:227], off
	v_lshl_add_u64 v[226:227], s[22:23], 0, v[132:133]
	s_mov_b32 m0, s42
	s_nop 0
	global_load_lds_dwordx4 v[226:227], off
	s_waitcnt vmcnt(8)
	s_waitcnt lgkmcnt(0)
	s_setprio 1
	s_barrier
	v_mfma_f32_16x16x32_bf16 v[126:129], v[146:149], v[190:193], v[126:129]
	v_mfma_f32_16x16x32_bf16 v[126:129], v[150:153], v[194:197], v[126:129]
	v_mfma_f32_16x16x32_bf16 v[110:113], v[150:153], v[202:205], v[110:113]
	v_mfma_f32_16x16x32_bf16 v[110:113], v[146:149], v[198:201], v[110:113]
	v_mfma_f32_16x16x32_bf16 v[94:97], v[146:149], v[206:209], v[94:97]
	v_mfma_f32_16x16x32_bf16 v[94:97], v[150:153], v[228:231], v[94:97]
	v_mfma_f32_16x16x32_bf16 v[78:81], v[150:153], v[236:239], v[78:81]
	v_mfma_f32_16x16x32_bf16 v[78:81], v[146:149], v[232:235], v[78:81]
	v_mfma_f32_16x16x32_bf16 v[70:73], v[154:157], v[232:235], v[70:73]
	v_mfma_f32_16x16x32_bf16 v[70:73], v[158:161], v[236:239], v[70:73]
	v_mfma_f32_16x16x32_bf16 v[86:89], v[158:161], v[228:231], v[86:89]
	v_mfma_f32_16x16x32_bf16 v[86:89], v[154:157], v[206:209], v[86:89]
	v_mfma_f32_16x16x32_bf16 v[102:105], v[154:157], v[198:201], v[102:105]
	v_mfma_f32_16x16x32_bf16 v[102:105], v[158:161], v[202:205], v[102:105]
	v_mfma_f32_16x16x32_bf16 v[118:121], v[158:161], v[194:197], v[118:121]
	v_mfma_f32_16x16x32_bf16 v[118:121], v[154:157], v[190:193], v[118:121]
	v_mfma_f32_16x16x32_bf16 v[122:125], v[162:165], v[190:193], v[122:125]
	v_mfma_f32_16x16x32_bf16 v[122:125], v[166:169], v[194:197], v[122:125]
	v_mfma_f32_16x16x32_bf16 v[106:109], v[166:169], v[202:205], v[106:109]
	v_mfma_f32_16x16x32_bf16 v[106:109], v[162:165], v[198:201], v[106:109]
	v_mfma_f32_16x16x32_bf16 v[90:93], v[162:165], v[206:209], v[90:93]
	v_mfma_f32_16x16x32_bf16 v[90:93], v[166:169], v[228:231], v[90:93]
	v_mfma_f32_16x16x32_bf16 v[74:77], v[166:169], v[236:239], v[74:77]
	v_mfma_f32_16x16x32_bf16 v[74:77], v[162:165], v[232:235], v[74:77]
	v_mfma_f32_16x16x32_bf16 v[66:69], v[170:173], v[232:235], v[66:69]
	v_mfma_f32_16x16x32_bf16 v[66:69], v[178:181], v[236:239], v[66:69]
	v_mfma_f32_16x16x32_bf16 v[82:85], v[178:181], v[228:231], v[82:85]
	v_mfma_f32_16x16x32_bf16 v[82:85], v[170:173], v[206:209], v[82:85]
	v_mfma_f32_16x16x32_bf16 v[98:101], v[170:173], v[198:201], v[98:101]
	v_mfma_f32_16x16x32_bf16 v[98:101], v[178:181], v[202:205], v[98:101]
	v_mfma_f32_16x16x32_bf16 v[114:117], v[178:181], v[194:197], v[114:117]
	v_mfma_f32_16x16x32_bf16 v[114:117], v[170:173], v[190:193], v[114:117]
	s_barrier
	s_setprio 0
	s_add_i32 s22, s53, s26
	v_lshl_add_u64 v[140:141], v[140:141], 0, s[34:35]
	s_mov_b32 m0, s22
	s_nop 0
	global_load_lds_dwordx4 v[140:141], off
	ds_read_b128 v[190:193], v145 offset:49152
	ds_read_b128 v[194:197], v145 offset:50176
	s_add_i32 m0, s22, 0x2000
	s_add_u32 s18, s18, 0x100080
	v_lshl_add_u64 v[140:141], v[186:187], 0, s[34:35]
	s_addc_u32 s19, s19, 0
	s_add_i32 s22, s54, s26
	global_load_lds_dwordx4 v[140:141], off
	ds_read_b128 v[198:201], v145 offset:51200
	ds_read_b128 v[202:205], v145 offset:52224
	v_lshl_add_u64 v[140:141], s[18:19], 0, v[0:1]
	s_mov_b32 m0, s22
	s_nop 0
	global_load_lds_dwordx4 v[140:141], off
	ds_read_b128 v[206:209], v145 offset:53248
	ds_read_b128 v[228:231], v145 offset:54272
	v_lshl_add_u64 v[140:141], s[18:19], 0, v[130:131]
	s_add_i32 m0, s22, 0x2000
	s_nop 0
	global_load_lds_dwordx4 v[140:141], off
	ds_read_b128 v[232:235], v145 offset:55296
	ds_read_b128 v[236:239], v145 offset:56320
	v_lshl_add_u64 v[140:141], v[188:189], 0, s[34:35]
	s_mov_b32 m0, s43
	s_nop 0
	global_load_lds_dwordx4 v[140:141], off
	s_add_i32 s52, s52, 2
	s_add_u32 s16, s16, 0x100
	s_addc_u32 s17, s17, 0
	s_add_u32 s50, s50, 0x100
	s_addc_u32 s51, s51, 0
	s_add_u32 s18, s16, 0xfff00080
	s_addc_u32 s19, s17, -1
	s_cmp_eq_u32 s52, 60
	s_cselect_b32 s23, s7, s19
	s_cselect_b32 s22, s48, s18
	s_cselect_b32 s19, s5, s51
	s_cselect_b32 s18, s49, s50
	v_lshl_add_u64 v[140:141], v[210:211], 0, s[34:35]
	s_mov_b32 m0, s44
	s_nop 0
	global_load_lds_dwordx4 v[140:141], off
	s_waitcnt vmcnt(8)
	s_waitcnt lgkmcnt(0)
	s_setprio 1
	s_barrier
	v_mfma_f32_16x16x32_bf16 v[62:65], v[146:149], v[190:193], v[62:65]
	v_mfma_f32_16x16x32_bf16 v[62:65], v[150:153], v[194:197], v[62:65]
	v_mfma_f32_16x16x32_bf16 v[46:49], v[150:153], v[202:205], v[46:49]
	v_mfma_f32_16x16x32_bf16 v[46:49], v[146:149], v[198:201], v[46:49]
	v_mfma_f32_16x16x32_bf16 v[30:33], v[146:149], v[206:209], v[30:33]
	v_mfma_f32_16x16x32_bf16 v[30:33], v[150:153], v[228:231], v[30:33]
	v_mfma_f32_16x16x32_bf16 v[14:17], v[150:153], v[236:239], v[14:17]
	v_mfma_f32_16x16x32_bf16 v[14:17], v[146:149], v[232:235], v[14:17]
	v_mfma_f32_16x16x32_bf16 v[6:9], v[154:157], v[232:235], v[6:9]
	v_mfma_f32_16x16x32_bf16 v[6:9], v[158:161], v[236:239], v[6:9]
	v_mfma_f32_16x16x32_bf16 v[22:25], v[158:161], v[228:231], v[22:25]
	v_mfma_f32_16x16x32_bf16 v[22:25], v[154:157], v[206:209], v[22:25]
	v_mfma_f32_16x16x32_bf16 v[38:41], v[154:157], v[198:201], v[38:41]
	v_mfma_f32_16x16x32_bf16 v[38:41], v[158:161], v[202:205], v[38:41]
	v_mfma_f32_16x16x32_bf16 v[54:57], v[158:161], v[194:197], v[54:57]
	v_mfma_f32_16x16x32_bf16 v[54:57], v[154:157], v[190:193], v[54:57]
	v_mfma_f32_16x16x32_bf16 v[58:61], v[162:165], v[190:193], v[58:61]
	v_mfma_f32_16x16x32_bf16 v[58:61], v[166:169], v[194:197], v[58:61]
	v_mfma_f32_16x16x32_bf16 v[42:45], v[166:169], v[202:205], v[42:45]
	v_mfma_f32_16x16x32_bf16 v[42:45], v[162:165], v[198:201], v[42:45]
	v_mfma_f32_16x16x32_bf16 v[26:29], v[162:165], v[206:209], v[26:29]
	v_mfma_f32_16x16x32_bf16 v[26:29], v[166:169], v[228:231], v[26:29]
	v_mfma_f32_16x16x32_bf16 v[10:13], v[166:169], v[236:239], v[10:13]
	v_mfma_f32_16x16x32_bf16 v[10:13], v[162:165], v[232:235], v[10:13]
	v_mfma_f32_16x16x32_bf16 v[2:5], v[170:173], v[232:235], v[2:5]
	v_mfma_f32_16x16x32_bf16 v[2:5], v[178:181], v[236:239], v[2:5]
	v_mfma_f32_16x16x32_bf16 v[18:21], v[178:181], v[228:231], v[18:21]
	v_mfma_f32_16x16x32_bf16 v[18:21], v[170:173], v[206:209], v[18:21]
	v_mfma_f32_16x16x32_bf16 v[34:37], v[170:173], v[198:201], v[34:37]
	v_mfma_f32_16x16x32_bf16 v[34:37], v[178:181], v[202:205], v[34:37]
	v_mfma_f32_16x16x32_bf16 v[50:53], v[178:181], v[194:197], v[50:53]
	v_mfma_f32_16x16x32_bf16 v[50:53], v[170:173], v[190:193], v[50:53]
	s_barrier
	s_setprio 0
	s_cmp_gt_u32 s52, 61
	s_cbranch_scc0 .LBB0_721
	s_and_b64 vcc, exec, s[2:3]
	s_cbranch_vccz .LBB0_724
	s_barrier

.LBB0_804:
	s_add_u32 s46, s16, 0x100
	s_addc_u32 s47, s17, 0
	s_mov_b32 s48, -2
	s_add_u32 s16, s14, 0x100
	s_addc_u32 s17, s15, 0
	s_cmpk_eq_i32 s48, 0xa8
	s_cselect_b32 s23, s5, s17
	s_cselect_b32 s22, s4, s16
	s_cselect_b32 s19, s9, s47
	s_cselect_b32 s18, s8, s46
.LBB0_805:
	s_add_i32 s49, 0, 0x10000
	v_add_u32_e32 v140, s49, v143
	s_add_i32 s50, 0, 0x14000
	ds_read_b128 v[146:149], v140
	ds_read_b128 v[150:153], v140 offset:1024
	ds_read_b128 v[154:157], v140 offset:2048
	ds_read_b128 v[158:161], v140 offset:3072
	v_add_u32_e32 v140, s50, v143
	ds_read_b128 v[162:165], v140
	ds_read_b128 v[166:169], v140 offset:1024
	ds_read_b128 v[170:173], v140 offset:2048
	ds_read_b128 v[178:181], v140 offset:3072
	v_lshl_add_u64 v[140:141], s[14:15], 0, v[136:137]
	s_add_i32 m0, s31, 0xc000
	ds_read_b128 v[190:193], v145
	ds_read_b128 v[194:197], v145 offset:1024
	ds_read_b128 v[198:201], v145 offset:2048
	ds_read_b128 v[202:205], v145 offset:3072
	ds_read_b128 v[206:209], v145 offset:4096
	ds_read_b128 v[228:231], v145 offset:5120
	ds_read_b128 v[232:235], v145 offset:6144
	ds_read_b128 v[236:239], v145 offset:7168
	global_load_lds_dwordx4 v[140:141], off
	v_lshl_add_u64 v[140:141], s[14:15], 0, v[138:139]
	s_add_i32 m0, s31, 0xe000
	s_nop 0
	global_load_lds_dwordx4 v[140:141], off
	s_cmp_eq_u32 s48, -2
	s_cbranch_scc1 .Lz0_3_0
	s_waitcnt vmcnt(8)
	s_waitcnt lgkmcnt(0)
	s_setprio 1
	s_barrier
	v_mfma_f32_16x16x32_bf16 v[126:129], v[146:149], v[190:193], v[126:129]
	v_mfma_f32_16x16x32_bf16 v[126:129], v[150:153], v[194:197], v[126:129]
	v_mfma_f32_16x16x32_bf16 v[118:121], v[150:153], v[202:205], v[118:121]
	v_mfma_f32_16x16x32_bf16 v[118:121], v[146:149], v[198:201], v[118:121]
	v_mfma_f32_16x16x32_bf16 v[102:105], v[146:149], v[206:209], v[102:105]
	v_mfma_f32_16x16x32_bf16 v[102:105], v[150:153], v[228:231], v[102:105]
	v_mfma_f32_16x16x32_bf16 v[86:89], v[150:153], v[236:239], v[86:89]
	v_mfma_f32_16x16x32_bf16 v[86:89], v[146:149], v[232:235], v[86:89]
	v_mfma_f32_16x16x32_bf16 v[78:81], v[154:157], v[232:235], v[78:81]
	v_mfma_f32_16x16x32_bf16 v[78:81], v[158:161], v[236:239], v[78:81]
	v_mfma_f32_16x16x32_bf16 v[94:97], v[158:161], v[228:231], v[94:97]
	v_mfma_f32_16x16x32_bf16 v[94:97], v[154:157], v[206:209], v[94:97]
	v_mfma_f32_16x16x32_bf16 v[110:113], v[154:157], v[198:201], v[110:113]
	v_mfma_f32_16x16x32_bf16 v[110:113], v[158:161], v[202:205], v[110:113]
	v_mfma_f32_16x16x32_bf16 v[122:125], v[158:161], v[194:197], v[122:125]
	v_mfma_f32_16x16x32_bf16 v[122:125], v[154:157], v[190:193], v[122:125]
	v_mfma_f32_16x16x32_bf16 v[114:117], v[162:165], v[190:193], v[114:117]
	v_mfma_f32_16x16x32_bf16 v[114:117], v[166:169], v[194:197], v[114:117]
	v_mfma_f32_16x16x32_bf16 v[98:101], v[166:169], v[202:205], v[98:101]
	v_mfma_f32_16x16x32_bf16 v[98:101], v[162:165], v[198:201], v[98:101]
	v_mfma_f32_16x16x32_bf16 v[82:85], v[162:165], v[206:209], v[82:85]
	v_mfma_f32_16x16x32_bf16 v[82:85], v[166:169], v[228:231], v[82:85]
	v_mfma_f32_16x16x32_bf16 v[70:73], v[166:169], v[236:239], v[70:73]
	v_mfma_f32_16x16x32_bf16 v[70:73], v[162:165], v[232:235], v[70:73]
	v_mfma_f32_16x16x32_bf16 v[66:69], v[170:173], v[232:235], v[66:69]
	v_mfma_f32_16x16x32_bf16 v[66:69], v[178:181], v[236:239], v[66:69]
	v_mfma_f32_16x16x32_bf16 v[74:77], v[178:181], v[228:231], v[74:77]
	v_mfma_f32_16x16x32_bf16 v[74:77], v[170:173], v[206:209], v[74:77]
	v_mfma_f32_16x16x32_bf16 v[90:93], v[170:173], v[198:201], v[90:93]
	v_mfma_f32_16x16x32_bf16 v[90:93], v[178:181], v[202:205], v[90:93]
	v_mfma_f32_16x16x32_bf16 v[106:109], v[178:181], v[194:197], v[106:109]
	v_mfma_f32_16x16x32_bf16 v[106:109], v[170:173], v[190:193], v[106:109]
	s_barrier
	s_setprio 0

.Lz0_3_1_ret:
	s_add_i32 s49, 0, 0x18000
	s_add_i32 s50, 0, 0x1c000
	v_add_u32_e32 v158, s49, v143
	v_add_u32_e32 v175, s50, v143
	ds_read_b128 v[146:149], v158
	ds_read_b128 v[150:153], v158 offset:1024
	ds_read_b128 v[154:157], v158 offset:2048
	ds_read_b128 v[158:161], v158 offset:3072
	ds_read_b128 v[162:165], v175
	ds_read_b128 v[166:169], v175 offset:1024
	ds_read_b128 v[170:173], v175 offset:2048
	ds_read_b128 v[178:181], v175 offset:3072
	s_add_u32 s14, s22, 0x2b0000
	s_addc_u32 s15, s23, 0
	s_mov_b32 m0, s37
	v_lshl_add_u64 v[226:227], s[14:15], 0, v[134:135]
	ds_read_b128 v[190:193], v145 offset:32768
	ds_read_b128 v[194:197], v145 offset:33792
	ds_read_b128 v[198:201], v145 offset:34816
	ds_read_b128 v[202:205], v145 offset:35840
	ds_read_b128 v[206:209], v145 offset:36864
	ds_read_b128 v[228:231], v145 offset:37888
	ds_read_b128 v[232:235], v145 offset:38912
	ds_read_b128 v[236:239], v145 offset:39936
	global_load_lds_dwordx4 v[226:227], off
	v_lshl_add_u64 v[226:227], s[14:15], 0, v[132:133]
	s_mov_b32 m0, s38
	s_nop 0
	global_load_lds_dwordx4 v[226:227], off
	s_waitcnt vmcnt(8)
	s_waitcnt lgkmcnt(0)
	s_setprio 1
	s_barrier
	v_mfma_f32_16x16x32_bf16 v[126:129], v[146:149], v[190:193], v[126:129]
	v_mfma_f32_16x16x32_bf16 v[126:129], v[150:153], v[194:197], v[126:129]
	v_mfma_f32_16x16x32_bf16 v[118:121], v[150:153], v[202:205], v[118:121]
	v_mfma_f32_16x16x32_bf16 v[118:121], v[146:149], v[198:201], v[118:121]
	v_mfma_f32_16x16x32_bf16 v[102:105], v[146:149], v[206:209], v[102:105]
	v_mfma_f32_16x16x32_bf16 v[102:105], v[150:153], v[228:231], v[102:105]
	v_mfma_f32_16x16x32_bf16 v[86:89], v[150:153], v[236:239], v[86:89]
	v_mfma_f32_16x16x32_bf16 v[86:89], v[146:149], v[232:235], v[86:89]
	v_mfma_f32_16x16x32_bf16 v[78:81], v[154:157], v[232:235], v[78:81]
	v_mfma_f32_16x16x32_bf16 v[78:81], v[158:161], v[236:239], v[78:81]
	v_mfma_f32_16x16x32_bf16 v[94:97], v[158:161], v[228:231], v[94:97]
	v_mfma_f32_16x16x32_bf16 v[94:97], v[154:157], v[206:209], v[94:97]
	v_mfma_f32_16x16x32_bf16 v[110:113], v[154:157], v[198:201], v[110:113]
	v_mfma_f32_16x16x32_bf16 v[110:113], v[158:161], v[202:205], v[110:113]
	v_mfma_f32_16x16x32_bf16 v[122:125], v[158:161], v[194:197], v[122:125]
	v_mfma_f32_16x16x32_bf16 v[122:125], v[154:157], v[190:193], v[122:125]
	v_mfma_f32_16x16x32_bf16 v[114:117], v[162:165], v[190:193], v[114:117]
	v_mfma_f32_16x16x32_bf16 v[114:117], v[166:169], v[194:197], v[114:117]
	v_mfma_f32_16x16x32_bf16 v[98:101], v[166:169], v[202:205], v[98:101]
	v_mfma_f32_16x16x32_bf16 v[98:101], v[162:165], v[198:201], v[98:101]
	v_mfma_f32_16x16x32_bf16 v[82:85], v[162:165], v[206:209], v[82:85]
	v_mfma_f32_16x16x32_bf16 v[82:85], v[166:169], v[228:231], v[82:85]
	v_mfma_f32_16x16x32_bf16 v[70:73], v[166:169], v[236:239], v[70:73]
	v_mfma_f32_16x16x32_bf16 v[70:73], v[162:165], v[232:235], v[70:73]
	v_mfma_f32_16x16x32_bf16 v[66:69], v[170:173], v[232:235], v[66:69]
	v_mfma_f32_16x16x32_bf16 v[66:69], v[178:181], v[236:239], v[66:69]
	v_mfma_f32_16x16x32_bf16 v[74:77], v[178:181], v[228:231], v[74:77]
	v_mfma_f32_16x16x32_bf16 v[74:77], v[170:173], v[206:209], v[74:77]
	v_mfma_f32_16x16x32_bf16 v[90:93], v[170:173], v[198:201], v[90:93]
	v_mfma_f32_16x16x32_bf16 v[90:93], v[178:181], v[202:205], v[90:93]
	v_mfma_f32_16x16x32_bf16 v[106:109], v[178:181], v[194:197], v[106:109]
	v_mfma_f32_16x16x32_bf16 v[106:109], v[170:173], v[190:193], v[106:109]
	s_barrier
	s_setprio 0
	s_add_i32 s14, s49, s26
	v_lshl_add_u64 v[140:141], v[140:141], 0, s[34:35]
	s_mov_b32 m0, s14
	s_nop 0
	global_load_lds_dwordx4 v[140:141], off
	ds_read_b128 v[190:193], v145 offset:49152
	ds_read_b128 v[194:197], v145 offset:50176
	s_add_i32 m0, s14, 0x2000
	s_add_u32 s14, s18, 0x2b0080
	v_lshl_add_u64 v[140:141], v[186:187], 0, s[34:35]
	s_addc_u32 s15, s19, 0
	s_add_i32 s18, s50, s26
	global_load_lds_dwordx4 v[140:141], off
	ds_read_b128 v[198:201], v145 offset:51200
	ds_read_b128 v[202:205], v145 offset:52224
	v_lshl_add_u64 v[140:141], s[14:15], 0, v[0:1]
	s_mov_b32 m0, s18
	s_nop 0
	global_load_lds_dwordx4 v[140:141], off
	ds_read_b128 v[206:209], v145 offset:53248
	ds_read_b128 v[228:231], v145 offset:54272
	v_lshl_add_u64 v[140:141], s[14:15], 0, v[130:131]
	s_add_i32 m0, s18, 0x2000
	s_nop 0
	global_load_lds_dwordx4 v[140:141], off
	ds_read_b128 v[232:235], v145 offset:55296
	ds_read_b128 v[236:239], v145 offset:56320
	v_lshl_add_u64 v[140:141], v[188:189], 0, s[34:35]
	s_mov_b32 m0, s39
	s_nop 0
	global_load_lds_dwordx4 v[140:141], off
	s_add_i32 s48, s48, 2
	s_add_u32 s46, s46, 0x100
	s_addc_u32 s47, s47, 0
	s_mov_b64 s[14:15], s[16:17]
	s_add_u32 s16, s14, 0x100
	s_addc_u32 s17, s15, 0
	s_cmpk_eq_i32 s48, 0xa8
	s_cselect_b32 s23, s5, s17
	s_cselect_b32 s22, s4, s16
	s_cselect_b32 s19, s9, s47
	s_cselect_b32 s18, s8, s46
	v_lshl_add_u64 v[140:141], v[210:211], 0, s[34:35]
	s_mov_b32 m0, s40
	s_nop 0
	global_load_lds_dwordx4 v[140:141], off
	s_waitcnt vmcnt(8)
	s_waitcnt lgkmcnt(0)
	s_setprio 1
	s_barrier
	v_mfma_f32_16x16x32_bf16 v[62:65], v[146:149], v[190:193], v[62:65]
	v_mfma_f32_16x16x32_bf16 v[62:65], v[150:153], v[194:197], v[62:65]
	v_mfma_f32_16x16x32_bf16 v[54:57], v[150:153], v[202:205], v[54:57]
	v_mfma_f32_16x16x32_bf16 v[54:57], v[146:149], v[198:201], v[54:57]
	v_mfma_f32_16x16x32_bf16 v[38:41], v[146:149], v[206:209], v[38:41]
	v_mfma_f32_16x16x32_bf16 v[38:41], v[150:153], v[228:231], v[38:41]
	v_mfma_f32_16x16x32_bf16 v[22:25], v[150:153], v[236:239], v[22:25]
	v_mfma_f32_16x16x32_bf16 v[22:25], v[146:149], v[232:235], v[22:25]
	v_mfma_f32_16x16x32_bf16 v[14:17], v[154:157], v[232:235], v[14:17]
	v_mfma_f32_16x16x32_bf16 v[14:17], v[158:161], v[236:239], v[14:17]
	v_mfma_f32_16x16x32_bf16 v[30:33], v[158:161], v[228:231], v[30:33]
	v_mfma_f32_16x16x32_bf16 v[30:33], v[154:157], v[206:209], v[30:33]
	v_mfma_f32_16x16x32_bf16 v[46:49], v[154:157], v[198:201], v[46:49]
	v_mfma_f32_16x16x32_bf16 v[46:49], v[158:161], v[202:205], v[46:49]
	v_mfma_f32_16x16x32_bf16 v[58:61], v[158:161], v[194:197], v[58:61]
	v_mfma_f32_16x16x32_bf16 v[58:61], v[154:157], v[190:193], v[58:61]
	v_mfma_f32_16x16x32_bf16 v[50:53], v[162:165], v[190:193], v[50:53]
	v_mfma_f32_16x16x32_bf16 v[50:53], v[166:169], v[194:197], v[50:53]
	v_mfma_f32_16x16x32_bf16 v[34:37], v[166:169], v[202:205], v[34:37]
	v_mfma_f32_16x16x32_bf16 v[34:37], v[162:165], v[198:201], v[34:37]
	v_mfma_f32_16x16x32_bf16 v[18:21], v[162:165], v[206:209], v[18:21]
	v_mfma_f32_16x16x32_bf16 v[18:21], v[166:169], v[228:231], v[18:21]
	v_mfma_f32_16x16x32_bf16 v[6:9], v[166:169], v[236:239], v[6:9]
	v_mfma_f32_16x16x32_bf16 v[6:9], v[162:165], v[232:235], v[6:9]
	v_mfma_f32_16x16x32_bf16 v[2:5], v[170:173], v[232:235], v[2:5]
	v_mfma_f32_16x16x32_bf16 v[2:5], v[178:181], v[236:239], v[2:5]
	v_mfma_f32_16x16x32_bf16 v[10:13], v[178:181], v[228:231], v[10:13]
	v_mfma_f32_16x16x32_bf16 v[10:13], v[170:173], v[206:209], v[10:13]
	v_mfma_f32_16x16x32_bf16 v[26:29], v[170:173], v[198:201], v[26:29]
	v_mfma_f32_16x16x32_bf16 v[26:29], v[178:181], v[202:205], v[26:29]
	v_mfma_f32_16x16x32_bf16 v[42:45], v[178:181], v[194:197], v[42:45]
	v_mfma_f32_16x16x32_bf16 v[42:45], v[170:173], v[190:193], v[42:45]
	s_barrier
	s_setprio 0
	s_cmpk_gt_u32 s48, 0xa9
	s_cbranch_scc0 .LBB0_805
	s_and_b64 vcc, exec, s[6:7]
	s_cbranch_vccz .LBB0_808
	s_barrier
